# attention query boundary: next query's first sub-block addresses/key indices computed in the last sub-block and its LDS-DMA requested right after the loop, per-query epilogue and setup run under it
# speedup vs baseline: 1.0038x; 1.0005x over previous
.Latt_skipq:
	s_mov_b32 s30, 0
	v_mov_b32_e32 v68, 0
	v_mov_b32_e32 v69, v72
	v_mov_b32_e32 v70, v72
	v_mov_b32_e32 v71, v72
	v_mov_b32_e32 v24, 0
	v_mov_b32_e32 v25, v72
	v_mov_b32_e32 v26, v72
	v_mov_b32_e32 v27, v72
	v_mov_b32_e32 v64, 0
	v_mov_b32_e32 v65, v72
	v_mov_b32_e32 v66, v72
	v_mov_b32_e32 v67, v72
	v_mov_b32_e32 v60, 0
	v_mov_b32_e32 v61, v72
	v_mov_b32_e32 v62, v72
	v_mov_b32_e32 v63, v72
	v_mov_b32_e32 v56, 0
	v_mov_b32_e32 v57, v72
	v_mov_b32_e32 v58, v72
	v_mov_b32_e32 v59, v72
	v_mov_b32_e32 v52, 0
	v_mov_b32_e32 v53, v72
	v_mov_b32_e32 v54, v72
	v_mov_b32_e32 v55, v72
	v_mov_b32_e32 v48, 0
	v_mov_b32_e32 v49, v72
	v_mov_b32_e32 v50, v72
	v_mov_b32_e32 v51, v72
	v_mov_b32_e32 v44, 0
	v_mov_b32_e32 v45, v72
	v_mov_b32_e32 v46, v72
	v_mov_b32_e32 v47, v72
	v_mov_b32_e32 v40, 0
	v_mov_b32_e32 v41, v72
	v_mov_b32_e32 v42, v72
	v_mov_b32_e32 v43, v72
	v_mov_b32_e32 v28, 0
	v_mov_b32_e32 v29, v72
	v_mov_b32_e32 v30, v72
	v_mov_b32_e32 v31, v72
	v_mov_b32_e32 v20, 0
	v_mov_b32_e32 v21, v72
	v_mov_b32_e32 v22, v72
	v_mov_b32_e32 v23, v72
	v_mov_b32_e32 v16, 0
	v_mov_b32_e32 v17, v72
	v_mov_b32_e32 v18, v72
	v_mov_b32_e32 v19, v72
	v_mov_b32_e32 v12, 0
	v_mov_b32_e32 v13, v72
	v_mov_b32_e32 v14, v72
	v_mov_b32_e32 v15, v72
	v_mov_b32_e32 v8, 0
	v_mov_b32_e32 v9, v72
	v_mov_b32_e32 v10, v72
	v_mov_b32_e32 v11, v72
	v_mov_b32_e32 v4, 0
	v_mov_b32_e32 v5, v72
	v_mov_b32_e32 v6, v72
	v_mov_b32_e32 v7, v72
	v_mov_b32_e32 v0, 0
	v_mov_b32_e32 v1, v72
	v_mov_b32_e32 v2, v72
	v_mov_b32_e32 v3, v72
	s_cmp_lg_u32 s25, 1
	s_cbranch_scc1 .Latt_skipsetup
	v_and_b32_e32 v132, 63, v165
	v_and_b32_e32 v133, 15, v132
	v_lshrrev_b32_e32 v134, 4, v132
	v_and_b32_e32 v135, 7, v133
	v_lshlrev_b32_e32 v135, 1, v135
	s_lshl_b32 s0, s22, 14
	v_lshl_add_u32 v136, v133, 9, s0
	v_add_u32_e32 v137, 0, v134
	v_xor_b32_e32 v137, v137, v135
	v_lshl_add_u32 v88, v137, 4, v136
	v_add_u32_e32 v137, 4, v134
	v_xor_b32_e32 v137, v137, v135
	v_lshl_add_u32 v89, v137, 4, v136
	v_add_u32_e32 v137, 8, v134
	v_xor_b32_e32 v137, v137, v135
	v_lshl_add_u32 v90, v137, 4, v136
	v_add_u32_e32 v137, 12, v134
	v_xor_b32_e32 v137, v137, v135
	v_lshl_add_u32 v91, v137, 4, v136
	v_lshrrev_b32_e32 v137, 2, v133
	v_lshl_add_u32 v137, v134, 2, v137
	v_and_b32_e32 v138, 7, v137
	v_lshl_add_u32 v139, v137, 9, s0
	v_bfe_u32 v140, v133, 1, 1
	v_and_b32_e32 v141, 1, v133
	v_lshl_add_u32 v139, v141, 3, v139
	v_lshl_add_u32 v139, v140, 4, v139
	v_xor_b32_e32 v137, 0, v138
	v_lshl_add_u32 v92, v137, 5, v139
	v_xor_b32_e32 v137, 1, v138
	v_lshl_add_u32 v93, v137, 5, v139
	v_xor_b32_e32 v137, 2, v138
	v_lshl_add_u32 v94, v137, 5, v139
	v_xor_b32_e32 v137, 3, v138
	v_lshl_add_u32 v95, v137, 5, v139
	v_xor_b32_e32 v137, 4, v138
	v_lshl_add_u32 v96, v137, 5, v139
	v_xor_b32_e32 v137, 5, v138
	v_lshl_add_u32 v97, v137, 5, v139
	v_xor_b32_e32 v137, 6, v138
	v_lshl_add_u32 v98, v137, 5, v139
	v_xor_b32_e32 v137, 7, v138
	v_lshl_add_u32 v99, v137, 5, v139
	v_and_b32_e32 v137, 31, v132
	v_add_u32_e32 v138, 0, v115
	v_and_b32_e32 v138, 7, v138
	v_lshlrev_b32_e32 v138, 1, v138
	v_xor_b32_e32 v138, v138, v137
	v_lshlrev_b32_e32 v152, 4, v138
	v_add_u32_e32 v138, 2, v115
	v_and_b32_e32 v138, 7, v138
	v_lshlrev_b32_e32 v138, 1, v138
	v_xor_b32_e32 v138, v138, v137
	v_lshlrev_b32_e32 v153, 4, v138
	v_add_u32_e32 v138, 4, v115
	v_and_b32_e32 v138, 7, v138
	v_lshlrev_b32_e32 v138, 1, v138
	v_xor_b32_e32 v138, v138, v137
	v_lshlrev_b32_e32 v154, 4, v138
	v_add_u32_e32 v138, 6, v115
	v_and_b32_e32 v138, 7, v138
	v_lshlrev_b32_e32 v138, 1, v138
	v_xor_b32_e32 v138, v138, v137
	v_lshlrev_b32_e32 v155, 4, v138
	v_mov_b32_e32 v244, v124
	s_nop 1
	v_readlane_b32 s0, v244, 0
	v_readlane_b32 s1, v244, 1
	v_readlane_b32 vcc_lo, v244, 2
	v_readlane_b32 vcc_hi, v244, 3
	s_mov_b32 exec_lo, 0xffff
	s_mov_b32 exec_hi, 0x0
	v_mov_b32_e32 v164, s0
	v_mov_b32_e32 v166, s1
	v_mov_b32_e32 v168, vcc_lo
	v_mov_b32_e32 v169, vcc_hi
	s_mov_b64 exec, -1
	s_max_i32 s0, s0, 0
	s_max_i32 s1, s1, 0
	s_max_i32 vcc_lo, vcc_lo, 0
	s_max_i32 vcc_hi, vcc_hi, 0
	s_sub_i32 s1, s1, s0
	s_sub_i32 vcc_hi, vcc_hi, vcc_lo
	s_lshl_b32 s0, s0, 9
	s_lshl_b32 s1, s1, 9
	s_lshl_b32 vcc_lo, vcc_lo, 9
	s_lshl_b32 vcc_hi, vcc_hi, 9
	v_add_u32_e32 v156, s0, v152
	v_add_u32_e32 v157, vcc_lo, v153
	v_mad_i32_i24 v156, v115, s1, v156
	v_mad_i32_i24 v157, v115, vcc_hi, v157
	v_readlane_b32 s0, v244, 4
	v_readlane_b32 s1, v244, 5
	v_readlane_b32 vcc_lo, v244, 6
	v_readlane_b32 vcc_hi, v244, 7
	s_mov_b32 exec_lo, 0xffff0000
	s_mov_b32 exec_hi, 0x0
	v_mov_b32_e32 v164, s0
	v_mov_b32_e32 v166, s1
	v_mov_b32_e32 v168, vcc_lo
	v_mov_b32_e32 v169, vcc_hi
	s_mov_b64 exec, -1
	s_max_i32 s0, s0, 0
	s_max_i32 s1, s1, 0
	s_max_i32 vcc_lo, vcc_lo, 0
	s_max_i32 vcc_hi, vcc_hi, 0
	s_sub_i32 s1, s1, s0
	s_sub_i32 vcc_hi, vcc_hi, vcc_lo
	s_lshl_b32 s0, s0, 9
	s_lshl_b32 s1, s1, 9
	s_lshl_b32 vcc_lo, vcc_lo, 9
	s_lshl_b32 vcc_hi, vcc_hi, 9
	v_add_u32_e32 v158, s0, v154
	v_add_u32_e32 v159, vcc_lo, v155
	v_mad_i32_i24 v158, v115, s1, v158
	v_mad_i32_i24 v159, v115, vcc_hi, v159
	v_readlane_b32 s0, v244, 8
	v_readlane_b32 s1, v244, 9
	v_readlane_b32 vcc_lo, v244, 10
	v_readlane_b32 vcc_hi, v244, 11
	s_mov_b32 exec_lo, 0x0
	s_mov_b32 exec_hi, 0xffff
	v_mov_b32_e32 v164, s0
	v_mov_b32_e32 v166, s1
	v_mov_b32_e32 v168, vcc_lo
	v_mov_b32_e32 v169, vcc_hi
	s_mov_b64 exec, -1
	s_max_i32 s0, s0, 0
	s_max_i32 s1, s1, 0
	s_max_i32 vcc_lo, vcc_lo, 0
	s_max_i32 vcc_hi, vcc_hi, 0
	s_sub_i32 s1, s1, s0
	s_sub_i32 vcc_hi, vcc_hi, vcc_lo
	s_lshl_b32 s0, s0, 9
	s_lshl_b32 s1, s1, 9
	s_lshl_b32 vcc_lo, vcc_lo, 9
	s_lshl_b32 vcc_hi, vcc_hi, 9
	v_add_u32_e32 v160, s0, v152
	v_add_u32_e32 v161, vcc_lo, v153
	v_mad_i32_i24 v160, v115, s1, v160
	v_mad_i32_i24 v161, v115, vcc_hi, v161
	v_readlane_b32 s0, v244, 12
	v_readlane_b32 s1, v244, 13
	v_readlane_b32 vcc_lo, v244, 14
	v_readlane_b32 vcc_hi, v244, 15
	s_mov_b32 exec_lo, 0x0
	s_mov_b32 exec_hi, 0xffff0000
	v_mov_b32_e32 v164, s0
	v_mov_b32_e32 v166, s1
	v_mov_b32_e32 v168, vcc_lo
	v_mov_b32_e32 v169, vcc_hi
	s_mov_b64 exec, -1
	s_max_i32 s0, s0, 0
	s_max_i32 s1, s1, 0
	s_max_i32 vcc_lo, vcc_lo, 0
	s_max_i32 vcc_hi, vcc_hi, 0
	s_sub_i32 s1, s1, s0
	s_sub_i32 vcc_hi, vcc_hi, vcc_lo
	s_lshl_b32 s0, s0, 9
	s_lshl_b32 s1, s1, 9
	s_lshl_b32 vcc_lo, vcc_lo, 9
	s_lshl_b32 vcc_hi, vcc_hi, 9
	v_add_u32_e32 v162, s0, v154
	v_add_u32_e32 v163, vcc_lo, v155
	v_mad_i32_i24 v162, v115, s1, v162
	v_mad_i32_i24 v163, v115, vcc_hi, v163
	v_readlane_b32 s0, v244, 16
	v_readlane_b32 s1, v244, 17
	v_readlane_b32 vcc_lo, v244, 18
	v_readlane_b32 vcc_hi, v244, 19
	s_mov_b32 exec_lo, 0xffff
	s_mov_b32 exec_hi, 0x0
	v_mov_b32_e32 v170, s0
	v_mov_b32_e32 v176, s1
	v_mov_b32_e32 v177, vcc_lo
	v_mov_b32_e32 v191, vcc_hi
	s_mov_b64 exec, -1
	s_max_i32 s0, s0, 0
	s_max_i32 s1, s1, 0
	s_max_i32 vcc_lo, vcc_lo, 0
	s_max_i32 vcc_hi, vcc_hi, 0
	s_sub_i32 s1, s1, s0
	s_sub_i32 vcc_hi, vcc_hi, vcc_lo
	s_lshl_b32 s0, s0, 9
	s_lshl_b32 s1, s1, 9
	s_lshl_b32 vcc_lo, vcc_lo, 9
	s_lshl_b32 vcc_hi, vcc_hi, 9
	v_add_u32_e32 v144, s0, v152
	v_add_u32_e32 v145, vcc_lo, v153
	v_mad_i32_i24 v144, v115, s1, v144
	v_mad_i32_i24 v145, v115, vcc_hi, v145
	v_readlane_b32 s0, v244, 20
	v_readlane_b32 s1, v244, 21
	v_readlane_b32 vcc_lo, v244, 22
	v_readlane_b32 vcc_hi, v244, 23
	s_mov_b32 exec_lo, 0xffff0000
	s_mov_b32 exec_hi, 0x0
	v_mov_b32_e32 v170, s0
	v_mov_b32_e32 v176, s1
	v_mov_b32_e32 v177, vcc_lo
	v_mov_b32_e32 v191, vcc_hi
	s_mov_b64 exec, -1
	s_max_i32 s0, s0, 0
	s_max_i32 s1, s1, 0
	s_max_i32 vcc_lo, vcc_lo, 0
	s_max_i32 vcc_hi, vcc_hi, 0
	s_sub_i32 s1, s1, s0
	s_sub_i32 vcc_hi, vcc_hi, vcc_lo
	s_lshl_b32 s0, s0, 9
	s_lshl_b32 s1, s1, 9
	s_lshl_b32 vcc_lo, vcc_lo, 9
	s_lshl_b32 vcc_hi, vcc_hi, 9
	v_add_u32_e32 v146, s0, v154
	v_add_u32_e32 v147, vcc_lo, v155
	v_mad_i32_i24 v146, v115, s1, v146
	v_mad_i32_i24 v147, v115, vcc_hi, v147
	v_readlane_b32 s0, v244, 24
	v_readlane_b32 s1, v244, 25
	v_readlane_b32 vcc_lo, v244, 26
	v_readlane_b32 vcc_hi, v244, 27
	s_mov_b32 exec_lo, 0x0
	s_mov_b32 exec_hi, 0xffff
	v_mov_b32_e32 v170, s0
	v_mov_b32_e32 v176, s1
	v_mov_b32_e32 v177, vcc_lo
	v_mov_b32_e32 v191, vcc_hi
	s_mov_b64 exec, -1
	s_max_i32 s0, s0, 0
	s_max_i32 s1, s1, 0
	s_max_i32 vcc_lo, vcc_lo, 0
	s_max_i32 vcc_hi, vcc_hi, 0
	s_sub_i32 s1, s1, s0
	s_sub_i32 vcc_hi, vcc_hi, vcc_lo
	s_lshl_b32 s0, s0, 9
	s_lshl_b32 s1, s1, 9
	s_lshl_b32 vcc_lo, vcc_lo, 9
	s_lshl_b32 vcc_hi, vcc_hi, 9
	v_add_u32_e32 v172, s0, v152
	v_add_u32_e32 v173, vcc_lo, v153
	v_mad_i32_i24 v172, v115, s1, v172
	v_mad_i32_i24 v173, v115, vcc_hi, v173
	v_readlane_b32 s0, v244, 28
	v_readlane_b32 s1, v244, 29
	v_readlane_b32 vcc_lo, v244, 30
	v_readlane_b32 vcc_hi, v244, 31
	s_mov_b32 exec_lo, 0x0
	s_mov_b32 exec_hi, 0xffff0000
	v_mov_b32_e32 v170, s0
	v_mov_b32_e32 v176, s1
	v_mov_b32_e32 v177, vcc_lo
	v_mov_b32_e32 v191, vcc_hi
	s_mov_b64 exec, -1
	s_max_i32 s0, s0, 0
	s_max_i32 s1, s1, 0
	s_max_i32 vcc_lo, vcc_lo, 0
	s_max_i32 vcc_hi, vcc_hi, 0
	s_sub_i32 s1, s1, s0
	s_sub_i32 vcc_hi, vcc_hi, vcc_lo
	s_lshl_b32 s0, s0, 9
	s_lshl_b32 s1, s1, 9
	s_lshl_b32 vcc_lo, vcc_lo, 9
	s_lshl_b32 vcc_hi, vcc_hi, 9
	v_add_u32_e32 v174, s0, v154
	v_add_u32_e32 v175, vcc_lo, v155
	v_mad_i32_i24 v174, v115, s1, v174
	v_mad_i32_i24 v175, v115, vcc_hi, v175
.Latt_skipsetup:
.LBB0_136:
	v_mov_b32_e32 v129, v72
	s_cmp_lg_u32 s30, 0
	s_cbranch_scc1 .Latt_issue
	s_cmp_lg_u32 s25, 1
	s_cbranch_scc1 .Latt_noissue
.Latt_issue:
	v_readfirstlane_b32 s2, v108
	v_readfirstlane_b32 s3, v109
	s_lshl_b32 m0, s22, 14
	s_nop 4
	s_nop 0
	global_load_lds_dwordx4 v156, s[2:3]
	s_add_i32 m0, m0, 0x400
	s_nop 0
	global_load_lds_dwordx4 v157, s[2:3]
	s_add_i32 m0, m0, 0x400
	s_nop 0
	global_load_lds_dwordx4 v158, s[2:3]
	s_add_i32 m0, m0, 0x400
	s_nop 0
	global_load_lds_dwordx4 v159, s[2:3]
	s_add_i32 m0, m0, 0x400
	s_nop 0
	global_load_lds_dwordx4 v160, s[2:3]
	s_add_i32 m0, m0, 0x400
	s_nop 0
	global_load_lds_dwordx4 v161, s[2:3]
	s_add_i32 m0, m0, 0x400
	s_nop 0
	global_load_lds_dwordx4 v162, s[2:3]
	s_add_i32 m0, m0, 0x400
	s_nop 0
	global_load_lds_dwordx4 v163, s[2:3]
	s_add_i32 m0, m0, 0x400
	s_nop 0
	global_load_lds_dwordx4 v144, s[2:3]
	s_add_i32 m0, m0, 0x400
	s_nop 0
	global_load_lds_dwordx4 v145, s[2:3]
	s_add_i32 m0, m0, 0x400
	s_nop 0
	global_load_lds_dwordx4 v146, s[2:3]
	s_add_i32 m0, m0, 0x400
	s_nop 0
	global_load_lds_dwordx4 v147, s[2:3]
	s_add_i32 m0, m0, 0x400
	s_nop 0
	global_load_lds_dwordx4 v172, s[2:3]
	s_add_i32 m0, m0, 0x400
	s_nop 0
	global_load_lds_dwordx4 v173, s[2:3]
	s_add_i32 m0, m0, 0x400
	s_nop 0
	global_load_lds_dwordx4 v174, s[2:3]
	s_add_i32 m0, m0, 0x400
	s_nop 0
	global_load_lds_dwordx4 v175, s[2:3]
.Latt_noissue:
	s_waitcnt vmcnt(0)
	s_waitcnt lgkmcnt(7)
	v_cmp_lt_i32_e32 vcc, -1, v164
	s_waitcnt lgkmcnt(0)
	ds_read_b128 v[228:231], v88
	ds_read_b128 v[232:235], v89
	ds_read_b128 v[236:239], v90
	ds_read_b128 v[240:243], v91
	s_waitcnt lgkmcnt(3)
	v_mfma_f32_16x16x32_bf16 v[134:137], v[228:231], v[196:199], 0
	ds_read_b128 v[228:231], v88 offset:256
	s_waitcnt lgkmcnt(3)
	v_mfma_f32_16x16x32_bf16 v[134:137], v[232:235], v[200:203], v[134:137]
	ds_read_b128 v[232:235], v89 offset:256
	s_waitcnt lgkmcnt(3)
	v_mfma_f32_16x16x32_bf16 v[134:137], v[236:239], v[204:207], v[134:137]
	ds_read_b128 v[236:239], v90 offset:256
	s_waitcnt lgkmcnt(3)
	v_mfma_f32_16x16x32_bf16 v[134:137], v[240:243], v[208:211], v[134:137]
	ds_read_b128 v[240:243], v91 offset:256
	s_waitcnt lgkmcnt(3)
	v_mfma_f32_16x16x32_bf16 v[134:137], v[228:231], v[212:215], v[134:137]
	ds_read_b128 v[228:231], v88 offset:8192
	s_waitcnt lgkmcnt(3)
	v_mfma_f32_16x16x32_bf16 v[134:137], v[232:235], v[216:219], v[134:137]
	ds_read_b128 v[232:235], v89 offset:8192
	s_waitcnt lgkmcnt(3)
	v_mfma_f32_16x16x32_bf16 v[134:137], v[236:239], v[220:223], v[134:137]
	ds_read_b128 v[236:239], v90 offset:8192
	s_waitcnt lgkmcnt(3)
	v_mfma_f32_16x16x32_bf16 v[134:137], v[240:243], v[224:227], v[134:137]
	ds_read_b128 v[240:243], v91 offset:8192
	s_waitcnt lgkmcnt(3)
	v_mfma_f32_16x16x32_bf16 v[72:75], v[228:231], v[196:199], 0
	ds_read_b128 v[228:231], v88 offset:8448
	s_waitcnt lgkmcnt(3)
	v_mfma_f32_16x16x32_bf16 v[72:75], v[232:235], v[200:203], v[72:75]
	ds_read_b128 v[232:235], v89 offset:8448
	s_waitcnt lgkmcnt(3)
	v_mfma_f32_16x16x32_bf16 v[72:75], v[236:239], v[204:207], v[72:75]
	ds_read_b128 v[236:239], v90 offset:8448
	s_waitcnt lgkmcnt(3)
	v_mfma_f32_16x16x32_bf16 v[72:75], v[240:243], v[208:211], v[72:75]
	ds_read_b128 v[240:243], v91 offset:8448
	v_subrev_u32_e32 v80, s29, v170
	v_med3_i32 v80, v80, s4, v189
	v_lshl_add_u32 v80, v80, 6, v116
	ds_read_b32 v80, v80 offset:8192
	s_waitcnt lgkmcnt(4)
	v_mfma_f32_16x16x32_bf16 v[72:75], v[228:231], v[212:215], v[72:75]
	s_waitcnt lgkmcnt(3)
	v_mfma_f32_16x16x32_bf16 v[72:75], v[232:235], v[216:219], v[72:75]
	s_waitcnt lgkmcnt(2)
	v_mfma_f32_16x16x32_bf16 v[72:75], v[236:239], v[220:223], v[72:75]
	s_waitcnt lgkmcnt(1)
	v_mfma_f32_16x16x32_bf16 v[72:75], v[240:243], v[224:227], v[72:75]
	v_subrev_u32_e32 v76, s29, v164
	v_med3_i32 v76, v76, s4, v189
	v_subrev_u32_e32 v77, s29, v166
	v_lshl_add_u32 v76, v76, 6, v116
	v_med3_i32 v77, v77, s4, v189
	v_subrev_u32_e32 v78, s29, v168
	ds_read_b32 v76, v76 offset:8192
	v_lshl_add_u32 v77, v77, 6, v116
	v_med3_i32 v78, v78, s4, v189
	v_subrev_u32_e32 v79, s29, v169
	ds_read_b32 v77, v77 offset:8192
	v_lshl_add_u32 v78, v78, 6, v116
	v_med3_i32 v79, v79, s4, v189
	ds_read_b32 v78, v78 offset:8192
	v_lshl_add_u32 v79, v79, 6, v116
	ds_read_b32 v79, v79 offset:8192
	s_waitcnt lgkmcnt(3)
	v_fmac_f32_e32 v76, 0x3d800000, v134
	v_cndmask_b32_e32 v76, v190, v76, vcc
	s_waitcnt lgkmcnt(2)
	v_fmac_f32_e32 v77, 0x3d800000, v135
	v_cmp_lt_i32_e32 vcc, -1, v166
	s_waitcnt lgkmcnt(1)
	v_fmac_f32_e32 v78, 0x3d800000, v136
	s_waitcnt lgkmcnt(0)
	v_fmac_f32_e32 v79, 0x3d800000, v137
	v_cndmask_b32_e32 v77, v190, v77, vcc
	v_cmp_lt_i32_e32 vcc, -1, v168
	v_fmac_f32_e32 v80, 0x3d800000, v72
	s_nop 0
	v_cndmask_b32_e32 v78, v190, v78, vcc
	v_cmp_lt_i32_e32 vcc, -1, v169
	s_nop 1
	v_cndmask_b32_e32 v79, v190, v79, vcc
	v_cmp_lt_i32_e32 vcc, -1, v170
	v_max_f32_e32 v81, v78, v79
	s_nop 0
	v_cndmask_b32_e32 v72, v190, v80, vcc
	v_subrev_u32_e32 v80, s29, v176
	v_med3_i32 v80, v80, s4, v189
	v_lshl_add_u32 v80, v80, 6, v116
	ds_read_b32 v80, v80 offset:8192
	v_cmp_lt_i32_e32 vcc, -1, v176
	s_waitcnt lgkmcnt(0)
	v_fmac_f32_e32 v80, 0x3d800000, v73
	v_subrev_u32_e32 v73, s29, v177
	v_med3_i32 v73, v73, s4, v189
	v_lshl_add_u32 v73, v73, 6, v116
	ds_read_b32 v73, v73 offset:8192
	v_cndmask_b32_e32 v80, v190, v80, vcc
	v_cmp_lt_i32_e32 vcc, -1, v177
	s_waitcnt lgkmcnt(0)
	v_fmac_f32_e32 v73, 0x3d800000, v74
	v_cndmask_b32_e32 v74, v190, v73, vcc
	v_subrev_u32_e32 v73, s29, v191
	v_med3_i32 v73, v73, s4, v189
	v_lshl_add_u32 v73, v73, 6, v116
	ds_read_b32 v73, v73 offset:8192
	v_cmp_lt_i32_e32 vcc, -1, v191
	s_waitcnt lgkmcnt(0)
	v_fmac_f32_e32 v73, 0x3d800000, v75
	v_cndmask_b32_e32 v75, v190, v73, vcc
	s_add_i32 s2, s30, 1
	s_cmp_eq_u32 s2, 8
	s_cbranch_scc1 .Latt_qpf
	s_lshr_b32 s3, s2, 1
	s_cmp_eq_u32 s3, 2
	s_cselect_b64 vcc, -1, 0
	v_cndmask_b32_e32 v244, v127, v126, vcc
	s_cmp_eq_u32 s3, 1
	s_cselect_b64 vcc, -1, 0
	v_cndmask_b32_e32 v244, v244, v125, vcc
	s_cmp_eq_u32 s3, 0
	s_cselect_b64 vcc, -1, 0
	v_cndmask_b32_e32 v244, v244, v124, vcc
	s_bitcmp1_b32 s2, 0
	s_cbranch_scc1 .Latt_a_odd
	v_readlane_b32 s0, v244, 0
	v_readlane_b32 s1, v244, 1
	v_readlane_b32 vcc_lo, v244, 2
	v_readlane_b32 vcc_hi, v244, 3
	s_mov_b32 exec_lo, 0xffff
	s_mov_b32 exec_hi, 0x0
	v_mov_b32_e32 v164, s0
	v_mov_b32_e32 v166, s1
	v_mov_b32_e32 v168, vcc_lo
	v_mov_b32_e32 v169, vcc_hi
	s_mov_b64 exec, -1
	s_max_i32 s0, s0, 0
	s_max_i32 s1, s1, 0
	s_max_i32 vcc_lo, vcc_lo, 0
	s_max_i32 vcc_hi, vcc_hi, 0
	s_sub_i32 s1, s1, s0
	s_sub_i32 vcc_hi, vcc_hi, vcc_lo
	s_lshl_b32 s0, s0, 9
	s_lshl_b32 s1, s1, 9
	s_lshl_b32 vcc_lo, vcc_lo, 9
	s_lshl_b32 vcc_hi, vcc_hi, 9
	v_add_u32_e32 v156, s0, v152
	v_add_u32_e32 v157, vcc_lo, v153
	v_mad_i32_i24 v156, v115, s1, v156
	v_mad_i32_i24 v157, v115, vcc_hi, v157
	v_readlane_b32 s0, v244, 4
	v_readlane_b32 s1, v244, 5
	v_readlane_b32 vcc_lo, v244, 6
	v_readlane_b32 vcc_hi, v244, 7
	s_mov_b32 exec_lo, 0xffff0000
	s_mov_b32 exec_hi, 0x0
	v_mov_b32_e32 v164, s0
	v_mov_b32_e32 v166, s1
	v_mov_b32_e32 v168, vcc_lo
	v_mov_b32_e32 v169, vcc_hi
	s_mov_b64 exec, -1
	s_max_i32 s0, s0, 0
	s_max_i32 s1, s1, 0
	s_max_i32 vcc_lo, vcc_lo, 0
	s_max_i32 vcc_hi, vcc_hi, 0
	s_sub_i32 s1, s1, s0
	s_sub_i32 vcc_hi, vcc_hi, vcc_lo
	s_lshl_b32 s0, s0, 9
	s_lshl_b32 s1, s1, 9
	s_lshl_b32 vcc_lo, vcc_lo, 9
	s_lshl_b32 vcc_hi, vcc_hi, 9
	v_add_u32_e32 v158, s0, v154
	v_add_u32_e32 v159, vcc_lo, v155
	v_mad_i32_i24 v158, v115, s1, v158
	v_mad_i32_i24 v159, v115, vcc_hi, v159
	v_readlane_b32 s0, v244, 8
	v_readlane_b32 s1, v244, 9
	v_readlane_b32 vcc_lo, v244, 10
	v_readlane_b32 vcc_hi, v244, 11
	s_mov_b32 exec_lo, 0x0
	s_mov_b32 exec_hi, 0xffff
	v_mov_b32_e32 v164, s0
	v_mov_b32_e32 v166, s1
	v_mov_b32_e32 v168, vcc_lo
	v_mov_b32_e32 v169, vcc_hi
	s_mov_b64 exec, -1
	s_max_i32 s0, s0, 0
	s_max_i32 s1, s1, 0
	s_max_i32 vcc_lo, vcc_lo, 0
	s_max_i32 vcc_hi, vcc_hi, 0
	s_sub_i32 s1, s1, s0
	s_sub_i32 vcc_hi, vcc_hi, vcc_lo
	s_lshl_b32 s0, s0, 9
	s_lshl_b32 s1, s1, 9
	s_lshl_b32 vcc_lo, vcc_lo, 9
	s_lshl_b32 vcc_hi, vcc_hi, 9
	v_add_u32_e32 v160, s0, v152
	v_add_u32_e32 v161, vcc_lo, v153
	v_mad_i32_i24 v160, v115, s1, v160
	v_mad_i32_i24 v161, v115, vcc_hi, v161
	v_readlane_b32 s0, v244, 12
	v_readlane_b32 s1, v244, 13
	v_readlane_b32 vcc_lo, v244, 14
	v_readlane_b32 vcc_hi, v244, 15
	s_mov_b32 exec_lo, 0x0
	s_mov_b32 exec_hi, 0xffff0000
	v_mov_b32_e32 v164, s0
	v_mov_b32_e32 v166, s1
	v_mov_b32_e32 v168, vcc_lo
	v_mov_b32_e32 v169, vcc_hi
	s_mov_b64 exec, -1
	s_max_i32 s0, s0, 0
	s_max_i32 s1, s1, 0
	s_max_i32 vcc_lo, vcc_lo, 0
	s_max_i32 vcc_hi, vcc_hi, 0
	s_sub_i32 s1, s1, s0
	s_sub_i32 vcc_hi, vcc_hi, vcc_lo
	s_lshl_b32 s0, s0, 9
	s_lshl_b32 s1, s1, 9
	s_lshl_b32 vcc_lo, vcc_lo, 9
	s_lshl_b32 vcc_hi, vcc_hi, 9
	v_add_u32_e32 v162, s0, v154
	v_add_u32_e32 v163, vcc_lo, v155
	v_mad_i32_i24 v162, v115, s1, v162
	v_mad_i32_i24 v163, v115, vcc_hi, v163
	v_readlane_b32 s0, v244, 16
	v_readlane_b32 s1, v244, 17
	v_readlane_b32 vcc_lo, v244, 18
	v_readlane_b32 vcc_hi, v244, 19
	s_mov_b32 exec_lo, 0xffff
	s_mov_b32 exec_hi, 0x0
	v_mov_b32_e32 v170, s0
	v_mov_b32_e32 v176, s1
	v_mov_b32_e32 v177, vcc_lo
	v_mov_b32_e32 v191, vcc_hi
	s_mov_b64 exec, -1
	s_max_i32 s0, s0, 0
	s_max_i32 s1, s1, 0
	s_max_i32 vcc_lo, vcc_lo, 0
	s_max_i32 vcc_hi, vcc_hi, 0
	s_sub_i32 s1, s1, s0
	s_sub_i32 vcc_hi, vcc_hi, vcc_lo
	s_lshl_b32 s0, s0, 9
	s_lshl_b32 s1, s1, 9
	s_lshl_b32 vcc_lo, vcc_lo, 9
	s_lshl_b32 vcc_hi, vcc_hi, 9
	v_add_u32_e32 v144, s0, v152
	v_add_u32_e32 v145, vcc_lo, v153
	v_mad_i32_i24 v144, v115, s1, v144
	v_mad_i32_i24 v145, v115, vcc_hi, v145
	v_readlane_b32 s0, v244, 20
	v_readlane_b32 s1, v244, 21
	v_readlane_b32 vcc_lo, v244, 22
	v_readlane_b32 vcc_hi, v244, 23
	s_mov_b32 exec_lo, 0xffff0000
	s_mov_b32 exec_hi, 0x0
	v_mov_b32_e32 v170, s0
	v_mov_b32_e32 v176, s1
	v_mov_b32_e32 v177, vcc_lo
	v_mov_b32_e32 v191, vcc_hi
	s_mov_b64 exec, -1
	s_max_i32 s0, s0, 0
	s_max_i32 s1, s1, 0
	s_max_i32 vcc_lo, vcc_lo, 0
	s_max_i32 vcc_hi, vcc_hi, 0
	s_sub_i32 s1, s1, s0
	s_sub_i32 vcc_hi, vcc_hi, vcc_lo
	s_lshl_b32 s0, s0, 9
	s_lshl_b32 s1, s1, 9
	s_lshl_b32 vcc_lo, vcc_lo, 9
	s_lshl_b32 vcc_hi, vcc_hi, 9
	v_add_u32_e32 v146, s0, v154
	v_add_u32_e32 v147, vcc_lo, v155
	v_mad_i32_i24 v146, v115, s1, v146
	v_mad_i32_i24 v147, v115, vcc_hi, v147
	v_readlane_b32 s0, v244, 24
	v_readlane_b32 s1, v244, 25
	v_readlane_b32 vcc_lo, v244, 26
	v_readlane_b32 vcc_hi, v244, 27
	s_mov_b32 exec_lo, 0x0
	s_mov_b32 exec_hi, 0xffff
	v_mov_b32_e32 v170, s0
	v_mov_b32_e32 v176, s1
	v_mov_b32_e32 v177, vcc_lo
	v_mov_b32_e32 v191, vcc_hi
	s_mov_b64 exec, -1
	s_max_i32 s0, s0, 0
	s_max_i32 s1, s1, 0
	s_max_i32 vcc_lo, vcc_lo, 0
	s_max_i32 vcc_hi, vcc_hi, 0
	s_sub_i32 s1, s1, s0
	s_sub_i32 vcc_hi, vcc_hi, vcc_lo
	s_lshl_b32 s0, s0, 9
	s_lshl_b32 s1, s1, 9
	s_lshl_b32 vcc_lo, vcc_lo, 9
	s_lshl_b32 vcc_hi, vcc_hi, 9
	v_add_u32_e32 v172, s0, v152
	v_add_u32_e32 v173, vcc_lo, v153
	v_mad_i32_i24 v172, v115, s1, v172
	v_mad_i32_i24 v173, v115, vcc_hi, v173
	v_readlane_b32 s0, v244, 28
	v_readlane_b32 s1, v244, 29
	v_readlane_b32 vcc_lo, v244, 30
	v_readlane_b32 vcc_hi, v244, 31
	s_mov_b32 exec_lo, 0x0
	s_mov_b32 exec_hi, 0xffff0000
	v_mov_b32_e32 v170, s0
	v_mov_b32_e32 v176, s1
	v_mov_b32_e32 v177, vcc_lo
	v_mov_b32_e32 v191, vcc_hi
	s_mov_b64 exec, -1
	s_max_i32 s0, s0, 0
	s_max_i32 s1, s1, 0
	s_max_i32 vcc_lo, vcc_lo, 0
	s_max_i32 vcc_hi, vcc_hi, 0
	s_sub_i32 s1, s1, s0
	s_sub_i32 vcc_hi, vcc_hi, vcc_lo
	s_lshl_b32 s0, s0, 9
	s_lshl_b32 s1, s1, 9
	s_lshl_b32 vcc_lo, vcc_lo, 9
	s_lshl_b32 vcc_hi, vcc_hi, 9
	v_add_u32_e32 v174, s0, v154
	v_add_u32_e32 v175, vcc_lo, v155
	v_mad_i32_i24 v174, v115, s1, v174
	v_mad_i32_i24 v175, v115, vcc_hi, v175
	s_branch .Latt_a_done

.Latt_qpf:
	s_cmp_lt_i32 s38, 0
	s_cbranch_scc1 .Latt_a_done
	v_mad_u64_u32 v[132:133], s[0:1], s38, v188, v[100:101]
	global_load_dwordx4 v[196:199], v[132:133], off
	global_load_dwordx4 v[200:203], v[132:133], off offset:64
	global_load_dwordx4 v[204:207], v[132:133], off offset:128
	global_load_dwordx4 v[208:211], v[132:133], off offset:192
	global_load_dwordx4 v[212:215], v[132:133], off offset:256
	global_load_dwordx4 v[216:219], v[132:133], off offset:320
	global_load_dwordx4 v[220:223], v[132:133], off offset:384
	global_load_dwordx4 v[224:227], v[132:133], off offset:448
	v_mov_b32_e32 v244, v123
	s_nop 1
	v_readlane_b32 s0, v244, 0
	v_readlane_b32 s1, v244, 1
	v_readlane_b32 vcc_lo, v244, 2
	v_readlane_b32 vcc_hi, v244, 3
	s_mov_b32 exec_lo, 0xffff
	s_mov_b32 exec_hi, 0x0
	v_mov_b32_e32 v164, s0
	v_mov_b32_e32 v166, s1
	v_mov_b32_e32 v168, vcc_lo
	v_mov_b32_e32 v169, vcc_hi
	s_mov_b64 exec, -1
	s_max_i32 s0, s0, 0
	s_max_i32 s1, s1, 0
	s_max_i32 vcc_lo, vcc_lo, 0
	s_max_i32 vcc_hi, vcc_hi, 0
	s_sub_i32 s1, s1, s0
	s_sub_i32 vcc_hi, vcc_hi, vcc_lo
	s_lshl_b32 s0, s0, 9
	s_lshl_b32 s1, s1, 9
	s_lshl_b32 vcc_lo, vcc_lo, 9
	s_lshl_b32 vcc_hi, vcc_hi, 9
	v_add_u32_e32 v156, s0, v152
	v_add_u32_e32 v157, vcc_lo, v153
	v_mad_i32_i24 v156, v115, s1, v156
	v_mad_i32_i24 v157, v115, vcc_hi, v157
	v_readlane_b32 s0, v244, 4
	v_readlane_b32 s1, v244, 5
	v_readlane_b32 vcc_lo, v244, 6
	v_readlane_b32 vcc_hi, v244, 7
	s_mov_b32 exec_lo, 0xffff0000
	s_mov_b32 exec_hi, 0x0
	v_mov_b32_e32 v164, s0
	v_mov_b32_e32 v166, s1
	v_mov_b32_e32 v168, vcc_lo
	v_mov_b32_e32 v169, vcc_hi
	s_mov_b64 exec, -1
	s_max_i32 s0, s0, 0
	s_max_i32 s1, s1, 0
	s_max_i32 vcc_lo, vcc_lo, 0
	s_max_i32 vcc_hi, vcc_hi, 0
	s_sub_i32 s1, s1, s0
	s_sub_i32 vcc_hi, vcc_hi, vcc_lo
	s_lshl_b32 s0, s0, 9
	s_lshl_b32 s1, s1, 9
	s_lshl_b32 vcc_lo, vcc_lo, 9
	s_lshl_b32 vcc_hi, vcc_hi, 9
	v_add_u32_e32 v158, s0, v154
	v_add_u32_e32 v159, vcc_lo, v155
	v_mad_i32_i24 v158, v115, s1, v158
	v_mad_i32_i24 v159, v115, vcc_hi, v159
	v_readlane_b32 s0, v244, 8
	v_readlane_b32 s1, v244, 9
	v_readlane_b32 vcc_lo, v244, 10
	v_readlane_b32 vcc_hi, v244, 11
	s_mov_b32 exec_lo, 0x0
	s_mov_b32 exec_hi, 0xffff
	v_mov_b32_e32 v164, s0
	v_mov_b32_e32 v166, s1
	v_mov_b32_e32 v168, vcc_lo
	v_mov_b32_e32 v169, vcc_hi
	s_mov_b64 exec, -1
	s_max_i32 s0, s0, 0
	s_max_i32 s1, s1, 0
	s_max_i32 vcc_lo, vcc_lo, 0
	s_max_i32 vcc_hi, vcc_hi, 0
	s_sub_i32 s1, s1, s0
	s_sub_i32 vcc_hi, vcc_hi, vcc_lo
	s_lshl_b32 s0, s0, 9
	s_lshl_b32 s1, s1, 9
	s_lshl_b32 vcc_lo, vcc_lo, 9
	s_lshl_b32 vcc_hi, vcc_hi, 9
	v_add_u32_e32 v160, s0, v152
	v_add_u32_e32 v161, vcc_lo, v153
	v_mad_i32_i24 v160, v115, s1, v160
	v_mad_i32_i24 v161, v115, vcc_hi, v161
	v_readlane_b32 s0, v244, 12
	v_readlane_b32 s1, v244, 13
	v_readlane_b32 vcc_lo, v244, 14
	v_readlane_b32 vcc_hi, v244, 15
	s_mov_b32 exec_lo, 0x0
	s_mov_b32 exec_hi, 0xffff0000
	v_mov_b32_e32 v164, s0
	v_mov_b32_e32 v166, s1
	v_mov_b32_e32 v168, vcc_lo
	v_mov_b32_e32 v169, vcc_hi
	s_mov_b64 exec, -1
	s_max_i32 s0, s0, 0
	s_max_i32 s1, s1, 0
	s_max_i32 vcc_lo, vcc_lo, 0
	s_max_i32 vcc_hi, vcc_hi, 0
	s_sub_i32 s1, s1, s0
	s_sub_i32 vcc_hi, vcc_hi, vcc_lo
	s_lshl_b32 s0, s0, 9
	s_lshl_b32 s1, s1, 9
	s_lshl_b32 vcc_lo, vcc_lo, 9
	s_lshl_b32 vcc_hi, vcc_hi, 9
	v_add_u32_e32 v162, s0, v154
	v_add_u32_e32 v163, vcc_lo, v155
	v_mad_i32_i24 v162, v115, s1, v162
	v_mad_i32_i24 v163, v115, vcc_hi, v163
	v_readlane_b32 s0, v244, 16
	v_readlane_b32 s1, v244, 17
	v_readlane_b32 vcc_lo, v244, 18
	v_readlane_b32 vcc_hi, v244, 19
	s_mov_b32 exec_lo, 0xffff
	s_mov_b32 exec_hi, 0x0
	v_mov_b32_e32 v170, s0
	v_mov_b32_e32 v176, s1
	v_mov_b32_e32 v177, vcc_lo
	v_mov_b32_e32 v191, vcc_hi
	s_mov_b64 exec, -1
	s_max_i32 s0, s0, 0
	s_max_i32 s1, s1, 0
	s_max_i32 vcc_lo, vcc_lo, 0
	s_max_i32 vcc_hi, vcc_hi, 0
	s_sub_i32 s1, s1, s0
	s_sub_i32 vcc_hi, vcc_hi, vcc_lo
	s_lshl_b32 s0, s0, 9
	s_lshl_b32 s1, s1, 9
	s_lshl_b32 vcc_lo, vcc_lo, 9
	s_lshl_b32 vcc_hi, vcc_hi, 9
	v_add_u32_e32 v144, s0, v152
	v_add_u32_e32 v145, vcc_lo, v153
	v_mad_i32_i24 v144, v115, s1, v144
	v_mad_i32_i24 v145, v115, vcc_hi, v145
	v_readlane_b32 s0, v244, 20
	v_readlane_b32 s1, v244, 21
	v_readlane_b32 vcc_lo, v244, 22
	v_readlane_b32 vcc_hi, v244, 23
	s_mov_b32 exec_lo, 0xffff0000
	s_mov_b32 exec_hi, 0x0
	v_mov_b32_e32 v170, s0
	v_mov_b32_e32 v176, s1
	v_mov_b32_e32 v177, vcc_lo
	v_mov_b32_e32 v191, vcc_hi
	s_mov_b64 exec, -1
	s_max_i32 s0, s0, 0
	s_max_i32 s1, s1, 0
	s_max_i32 vcc_lo, vcc_lo, 0
	s_max_i32 vcc_hi, vcc_hi, 0
	s_sub_i32 s1, s1, s0
	s_sub_i32 vcc_hi, vcc_hi, vcc_lo
	s_lshl_b32 s0, s0, 9
	s_lshl_b32 s1, s1, 9
	s_lshl_b32 vcc_lo, vcc_lo, 9
	s_lshl_b32 vcc_hi, vcc_hi, 9
	v_add_u32_e32 v146, s0, v154
	v_add_u32_e32 v147, vcc_lo, v155
	v_mad_i32_i24 v146, v115, s1, v146
	v_mad_i32_i24 v147, v115, vcc_hi, v147
	v_readlane_b32 s0, v244, 24
	v_readlane_b32 s1, v244, 25
	v_readlane_b32 vcc_lo, v244, 26
	v_readlane_b32 vcc_hi, v244, 27
	s_mov_b32 exec_lo, 0x0
	s_mov_b32 exec_hi, 0xffff
	v_mov_b32_e32 v170, s0
	v_mov_b32_e32 v176, s1
	v_mov_b32_e32 v177, vcc_lo
	v_mov_b32_e32 v191, vcc_hi
	s_mov_b64 exec, -1
	s_max_i32 s0, s0, 0
	s_max_i32 s1, s1, 0
	s_max_i32 vcc_lo, vcc_lo, 0
	s_max_i32 vcc_hi, vcc_hi, 0
	s_sub_i32 s1, s1, s0
	s_sub_i32 vcc_hi, vcc_hi, vcc_lo
	s_lshl_b32 s0, s0, 9
	s_lshl_b32 s1, s1, 9
	s_lshl_b32 vcc_lo, vcc_lo, 9
	s_lshl_b32 vcc_hi, vcc_hi, 9
	v_add_u32_e32 v172, s0, v152
	v_add_u32_e32 v173, vcc_lo, v153
	v_mad_i32_i24 v172, v115, s1, v172
	v_mad_i32_i24 v173, v115, vcc_hi, v173
	v_readlane_b32 s0, v244, 28
	v_readlane_b32 s1, v244, 29
	v_readlane_b32 vcc_lo, v244, 30
	v_readlane_b32 vcc_hi, v244, 31
	s_mov_b32 exec_lo, 0x0
	s_mov_b32 exec_hi, 0xffff0000
	v_mov_b32_e32 v170, s0
	v_mov_b32_e32 v176, s1
	v_mov_b32_e32 v177, vcc_lo
	v_mov_b32_e32 v191, vcc_hi
	s_mov_b64 exec, -1
	s_max_i32 s0, s0, 0
	s_max_i32 s1, s1, 0
	s_max_i32 vcc_lo, vcc_lo, 0
	s_max_i32 vcc_hi, vcc_hi, 0
	s_sub_i32 s1, s1, s0
	s_sub_i32 vcc_hi, vcc_hi, vcc_lo
	s_lshl_b32 s0, s0, 9
	s_lshl_b32 s1, s1, 9
	s_lshl_b32 vcc_lo, vcc_lo, 9
	s_lshl_b32 vcc_hi, vcc_hi, 9
	v_add_u32_e32 v174, s0, v154
	v_add_u32_e32 v175, vcc_lo, v155
	v_mad_i32_i24 v174, v115, s1, v174
	v_mad_i32_i24 v175, v115, vcc_hi, v175
.Latt_a_done:
	v_max_f32_e32 v82, v74, v75
	v_max_f32_e32 v73, v76, v77
	v_max3_f32 v82, v72, v80, v82
	v_max3_f32 v73, v73, v81, v82
	v_mov_b32_e32 v81, v73
	s_nop 1
	v_permlane16_swap_b32 v81, v73
	v_max_f32_e32 v73, v73, v81
	v_mov_b32_e32 v81, v73
	s_nop 1
	v_permlane32_swap_b32 v81, v73
	v_max3_f32 v73, v128, v73, v81
	v_sub_f32_e32 v72, v72, v73
	v_mul_f32_e32 v72, 0x3fb8aa3b, v72
	v_sub_f32_e32 v76, v76, v73
	v_exp_f32_e32 v82, v72
	v_sub_f32_e32 v72, v80, v73
	v_mul_f32_e32 v76, 0x3fb8aa3b, v76
	v_sub_f32_e32 v77, v77, v73
	v_mul_f32_e32 v72, 0x3fb8aa3b, v72
	v_exp_f32_e32 v76, v76
	v_mul_f32_e32 v77, 0x3fb8aa3b, v77
	v_sub_f32_e32 v78, v78, v73
	v_exp_f32_e32 v80, v72
	v_sub_f32_e32 v72, v74, v73
	v_exp_f32_e32 v77, v77
	v_mul_f32_e32 v78, 0x3fb8aa3b, v78
	v_sub_f32_e32 v79, v79, v73
	v_mul_f32_e32 v72, 0x3fb8aa3b, v72
	v_exp_f32_e32 v78, v78
	v_mul_f32_e32 v79, 0x3fb8aa3b, v79
	v_exp_f32_e32 v83, v72
	v_sub_f32_e32 v72, v75, v73
	v_exp_f32_e32 v79, v79
	v_mul_f32_e32 v72, 0x3fb8aa3b, v72
	v_exp_f32_e32 v84, v72
	v_add_f32_e32 v72, 0, v76
	v_add_f32_e32 v72, v77, v72
	v_add_f32_e32 v72, v78, v72
	v_sub_f32_e32 v81, v128, v73
	v_add_f32_e32 v72, v79, v72
	v_mul_f32_e32 v81, 0x3fb8aa3b, v81
	v_add_f32_e32 v72, v82, v72
	v_exp_f32_e32 v86, v81
	v_add_f32_e32 v72, v80, v72
	v_add_f32_e32 v72, v83, v72
	v_cvt_pk_bf16_f32 v74, v76, v77
	v_cvt_pk_bf16_f32 v75, v78, v79
	v_cvt_pk_bf16_f32 v76, v82, v80
	v_cvt_pk_bf16_f32 v77, v83, v84
	ds_read_b64_tr_b16 v[80:81], v92 offset:8192
	ds_read_b64_tr_b16 v[78:79], v92
	ds_read_b64_tr_b16 v[82:83], v93
	v_pk_mul_f32 v[70:71], v[70:71], v[86:87] op_sel_hi:[1,0]
	v_pk_mul_f32 v[68:69], v[68:69], v[86:87] op_sel_hi:[1,0]
	v_add_f32_e32 v72, v84, v72
	ds_read_b64_tr_b16 v[84:85], v93 offset:8192
	s_waitcnt lgkmcnt(2)
	v_mfma_f32_16x16x32_bf16 v[68:71], v[78:81], v[74:77], v[68:71]
	ds_read_b64_tr_b16 v[78:79], v94
	ds_read_b64_tr_b16 v[80:81], v94 offset:8192
	v_pk_mul_f32 v[66:67], v[66:67], v[86:87] op_sel_hi:[1,0]
	v_pk_mul_f32 v[64:65], v[64:65], v[86:87] op_sel_hi:[1,0]
	v_pk_mul_f32 v[62:63], v[62:63], v[86:87] op_sel_hi:[1,0]
	v_pk_mul_f32 v[60:61], v[60:61], v[86:87] op_sel_hi:[1,0]
	s_waitcnt lgkmcnt(0)
	v_mfma_f32_16x16x32_bf16 v[64:67], v[78:81], v[74:77], v[64:67]
	ds_read_b64_tr_b16 v[78:79], v95
	ds_read_b64_tr_b16 v[80:81], v95 offset:8192
	v_pk_mul_f32 v[26:27], v[26:27], v[86:87] op_sel_hi:[1,0]
	v_pk_mul_f32 v[24:25], v[24:25], v[86:87] op_sel_hi:[1,0]
	s_waitcnt lgkmcnt(0)
	v_mfma_f32_16x16x32_bf16 v[60:63], v[78:81], v[74:77], v[60:63]
	v_mul_f32_e64 v58, v58, v86
	v_mul_f32_e64 v59, v59, v86
	v_pk_mul_f32 v[56:57], v[56:57], v[86:87] op_sel_hi:[1,0]
	v_pk_mul_f32 v[50:51], v[50:51], v[86:87] op_sel_hi:[1,0]
	v_mfma_f32_16x16x32_bf16 v[24:27], v[82:85], v[74:77], v[24:27]
	ds_read_b64_tr_b16 v[80:81], v96 offset:8192
	ds_read_b64_tr_b16 v[78:79], v96
	ds_read_b64_tr_b16 v[82:83], v97
	ds_read_b64_tr_b16 v[84:85], v97 offset:8192
	v_pk_mul_f32 v[48:49], v[48:49], v[86:87] op_sel_hi:[1,0]
	s_waitcnt lgkmcnt(2)
	v_mfma_f32_16x16x32_bf16 v[56:59], v[78:81], v[74:77], v[56:59]
	ds_read_b64_tr_b16 v[78:79], v98
	ds_read_b64_tr_b16 v[80:81], v98 offset:8192
	v_pk_mul_f32 v[54:55], v[54:55], v[86:87] op_sel_hi:[1,0]
	v_pk_mul_f32 v[52:53], v[52:53], v[86:87] op_sel_hi:[1,0]
	s_waitcnt lgkmcnt(0)
	v_mfma_f32_16x16x32_bf16 v[48:51], v[78:81], v[74:77], v[48:51]
	ds_read_b64_tr_b16 v[78:79], v99
	ds_read_b64_tr_b16 v[80:81], v99 offset:8192
	v_pk_mul_f32 v[46:47], v[46:47], v[86:87] op_sel_hi:[1,0]
	v_pk_mul_f32 v[44:45], v[44:45], v[86:87] op_sel_hi:[1,0]
	v_mfma_f32_16x16x32_bf16 v[52:55], v[82:85], v[74:77], v[52:55]
	v_mul_f32_e64 v42, v42, v86
	v_mul_f32_e64 v43, v43, v86
	v_pk_mul_f32 v[40:41], v[40:41], v[86:87] op_sel_hi:[1,0]
	v_pk_mul_f32 v[22:23], v[22:23], v[86:87] op_sel_hi:[1,0]
	s_waitcnt lgkmcnt(0)
	v_mfma_f32_16x16x32_bf16 v[44:47], v[78:81], v[74:77], v[44:47]
	ds_read_b64_tr_b16 v[80:81], v92 offset:8448
	ds_read_b64_tr_b16 v[78:79], v92 offset:256
	ds_read_b64_tr_b16 v[82:83], v93 offset:256
	ds_read_b64_tr_b16 v[84:85], v93 offset:8448
	v_pk_mul_f32 v[20:21], v[20:21], v[86:87] op_sel_hi:[1,0]
	s_waitcnt lgkmcnt(2)
	v_mfma_f32_16x16x32_bf16 v[40:43], v[78:81], v[74:77], v[40:43]
	ds_read_b64_tr_b16 v[78:79], v94 offset:256
	ds_read_b64_tr_b16 v[80:81], v94 offset:8448
	v_pk_mul_f32 v[30:31], v[30:31], v[86:87] op_sel_hi:[1,0]
	v_pk_mul_f32 v[28:29], v[28:29], v[86:87] op_sel_hi:[1,0]
	s_waitcnt lgkmcnt(0)
	v_mfma_f32_16x16x32_bf16 v[20:23], v[78:81], v[74:77], v[20:23]
	ds_read_b64_tr_b16 v[78:79], v95 offset:256
	ds_read_b64_tr_b16 v[80:81], v95 offset:8448
	v_pk_mul_f32 v[18:19], v[18:19], v[86:87] op_sel_hi:[1,0]
	v_pk_mul_f32 v[16:17], v[16:17], v[86:87] op_sel_hi:[1,0]
	v_mfma_f32_16x16x32_bf16 v[28:31], v[82:85], v[74:77], v[28:31]
	v_mul_f32_e64 v14, v14, v86
	v_mul_f32_e64 v15, v15, v86
	v_pk_mul_f32 v[12:13], v[12:13], v[86:87] op_sel_hi:[1,0]
	v_pk_mul_f32 v[6:7], v[6:7], v[86:87] op_sel_hi:[1,0]
	s_waitcnt lgkmcnt(0)
	v_mfma_f32_16x16x32_bf16 v[16:19], v[78:81], v[74:77], v[16:19]
	ds_read_b64_tr_b16 v[80:81], v96 offset:8448
	ds_read_b64_tr_b16 v[78:79], v96 offset:256
	ds_read_b64_tr_b16 v[82:83], v97 offset:256
	ds_read_b64_tr_b16 v[84:85], v97 offset:8448
	v_pk_mul_f32 v[4:5], v[4:5], v[86:87] op_sel_hi:[1,0]
	s_waitcnt lgkmcnt(2)
	v_mfma_f32_16x16x32_bf16 v[12:15], v[78:81], v[74:77], v[12:15]
	ds_read_b64_tr_b16 v[78:79], v98 offset:256
	ds_read_b64_tr_b16 v[80:81], v98 offset:8448
	v_pk_mul_f32 v[10:11], v[10:11], v[86:87] op_sel_hi:[1,0]
	v_pk_mul_f32 v[8:9], v[8:9], v[86:87] op_sel_hi:[1,0]
	s_waitcnt lgkmcnt(0)
	v_mfma_f32_16x16x32_bf16 v[4:7], v[78:81], v[74:77], v[4:7]
	ds_read_b64_tr_b16 v[78:79], v99 offset:256
	ds_read_b64_tr_b16 v[80:81], v99 offset:8448
	v_pk_mul_f32 v[2:3], v[2:3], v[86:87] op_sel_hi:[1,0]
	v_pk_mul_f32 v[0:1], v[0:1], v[86:87] op_sel_hi:[1,0]
	v_mfma_f32_16x16x32_bf16 v[8:11], v[82:85], v[74:77], v[8:11]
	s_waitcnt lgkmcnt(0)
	v_fmac_f32_e32 v72, v129, v86
	s_waitcnt lgkmcnt(0)
	v_mfma_f32_16x16x32_bf16 v[0:3], v[78:81], v[74:77], v[0:3]
	v_mov_b32_e32 v128, v73
	s_add_i32 s30, s30, 1
	s_add_i32 s28, s28, 32
	s_cmp_eq_u32 s30, 8
	s_cbranch_scc0 .LBB0_136
	s_cmp_lt_i32 s38, 0
	s_cbranch_scc1 .Latt_nonext
	v_readfirstlane_b32 s2, v108
	v_readfirstlane_b32 s3, v109
	s_lshl_b32 m0, s22, 14
	s_nop 4
	s_nop 0
	global_load_lds_dwordx4 v156, s[2:3]
	s_add_i32 m0, m0, 0x400
	s_nop 0
	global_load_lds_dwordx4 v157, s[2:3]
	s_add_i32 m0, m0, 0x400
	s_nop 0
	global_load_lds_dwordx4 v158, s[2:3]
	s_add_i32 m0, m0, 0x400
	s_nop 0
	global_load_lds_dwordx4 v159, s[2:3]
	s_add_i32 m0, m0, 0x400
	s_nop 0
	global_load_lds_dwordx4 v160, s[2:3]
	s_add_i32 m0, m0, 0x400
	s_nop 0
	global_load_lds_dwordx4 v161, s[2:3]
	s_add_i32 m0, m0, 0x400
	s_nop 0
	global_load_lds_dwordx4 v162, s[2:3]
	s_add_i32 m0, m0, 0x400
	s_nop 0
	global_load_lds_dwordx4 v163, s[2:3]
	s_add_i32 m0, m0, 0x400
	s_nop 0
	global_load_lds_dwordx4 v144, s[2:3]
	s_add_i32 m0, m0, 0x400
	s_nop 0
	global_load_lds_dwordx4 v145, s[2:3]
	s_add_i32 m0, m0, 0x400
	s_nop 0
	global_load_lds_dwordx4 v146, s[2:3]
	s_add_i32 m0, m0, 0x400
	s_nop 0
	global_load_lds_dwordx4 v147, s[2:3]
	s_add_i32 m0, m0, 0x400
	s_nop 0
	global_load_lds_dwordx4 v172, s[2:3]
	s_add_i32 m0, m0, 0x400
	s_nop 0
	global_load_lds_dwordx4 v173, s[2:3]
	s_add_i32 m0, m0, 0x400
	s_nop 0
	global_load_lds_dwordx4 v174, s[2:3]
	s_add_i32 m0, m0, 0x400
	s_nop 0
	global_load_lds_dwordx4 v175, s[2:3]
.Latt_nonext:
	ds_bpermute_b32 v73, v113, v72
	v_mov_b32_e32 v124, v123
	v_mov_b32_e32 v125, v122
	v_mov_b32_e32 v126, v121
	v_mov_b32_e32 v127, v120
	s_waitcnt lgkmcnt(0)
	v_add_f32_e32 v72, v72, v73
	ds_bpermute_b32 v73, v114, v72
	s_mov_b32 s2, s25
	s_waitcnt lgkmcnt(0)
	v_add_f32_e32 v72, v72, v73
	v_div_scale_f32 v73, s[0:1], v72, v72, 1.0
	v_rcp_f32_e32 v74, v73
	s_lshl_b64 s[0:1], s[76:77], 13
	s_mov_b32 s76, s38
	v_fma_f32 v75, -v73, v74, 1.0
	v_fmac_f32_e32 v74, v75, v74
	v_div_scale_f32 v75, vcc, 1.0, v72, 1.0
	v_mul_f32_e32 v76, v75, v74
	v_fma_f32 v77, -v73, v76, v75
	v_fmac_f32_e32 v76, v77, v74
	v_fma_f32 v73, -v73, v76, v75
	v_div_fmas_f32 v73, v73, v74, v76
	v_div_fixup_f32 v72, v73, v72, 1.0
	v_pk_mul_f32 v[24:25], v[24:25], v[72:73] op_sel_hi:[1,0]
	v_pk_mul_f32 v[26:27], v[26:27], v[72:73] op_sel_hi:[1,0]
	v_lshl_add_u64 v[74:75], v[104:105], 0, s[0:1]
	v_cvt_pk_bf16_f32 v24, v24, v25
	v_cvt_pk_bf16_f32 v25, v26, v27
	global_store_dwordx2 v[74:75], v[24:25], off offset:32
	v_pk_mul_f32 v[24:25], v[64:65], v[72:73] op_sel_hi:[1,0]
	v_pk_mul_f32 v[26:27], v[66:67], v[72:73] op_sel_hi:[1,0]
	v_cvt_pk_bf16_f32 v24, v24, v25
	v_cvt_pk_bf16_f32 v25, v26, v27
	global_store_dwordx2 v[74:75], v[24:25], off offset:64
	v_pk_mul_f32 v[24:25], v[60:61], v[72:73] op_sel_hi:[1,0]
	v_pk_mul_f32 v[26:27], v[62:63], v[72:73] op_sel_hi:[1,0]
	v_cvt_pk_bf16_f32 v24, v24, v25
	v_cvt_pk_bf16_f32 v25, v26, v27
	global_store_dwordx2 v[74:75], v[24:25], off offset:96
	v_pk_mul_f32 v[24:25], v[56:57], v[72:73] op_sel_hi:[1,0]
	v_pk_mul_f32 v[26:27], v[58:59], v[72:73] op_sel_hi:[1,0]
	v_cvt_pk_bf16_f32 v24, v24, v25
	v_cvt_pk_bf16_f32 v25, v26, v27
	global_store_dwordx2 v[74:75], v[24:25], off offset:128
	v_pk_mul_f32 v[24:25], v[52:53], v[72:73] op_sel_hi:[1,0]
	v_pk_mul_f32 v[26:27], v[54:55], v[72:73] op_sel_hi:[1,0]
	v_cvt_pk_bf16_f32 v24, v24, v25
	v_cvt_pk_bf16_f32 v25, v26, v27
	global_store_dwordx2 v[74:75], v[24:25], off offset:160
	v_pk_mul_f32 v[24:25], v[48:49], v[72:73] op_sel_hi:[1,0]
	v_pk_mul_f32 v[26:27], v[50:51], v[72:73] op_sel_hi:[1,0]
	v_cvt_pk_bf16_f32 v24, v24, v25
	v_cvt_pk_bf16_f32 v25, v26, v27
	global_store_dwordx2 v[74:75], v[24:25], off offset:192
	v_pk_mul_f32 v[24:25], v[44:45], v[72:73] op_sel_hi:[1,0]
	v_pk_mul_f32 v[26:27], v[46:47], v[72:73] op_sel_hi:[1,0]
	v_cvt_pk_bf16_f32 v24, v24, v25
	v_cvt_pk_bf16_f32 v25, v26, v27
	global_store_dwordx2 v[74:75], v[24:25], off offset:224
	v_pk_mul_f32 v[24:25], v[40:41], v[72:73] op_sel_hi:[1,0]
	v_pk_mul_f32 v[26:27], v[42:43], v[72:73] op_sel_hi:[1,0]
	v_cvt_pk_bf16_f32 v24, v24, v25
	v_cvt_pk_bf16_f32 v25, v26, v27
	v_pk_mul_f32 v[68:69], v[68:69], v[72:73] op_sel_hi:[1,0]
	v_pk_mul_f32 v[70:71], v[70:71], v[72:73] op_sel_hi:[1,0]
	global_store_dwordx2 v[74:75], v[24:25], off offset:256
	v_pk_mul_f32 v[24:25], v[28:29], v[72:73] op_sel_hi:[1,0]
	v_pk_mul_f32 v[26:27], v[30:31], v[72:73] op_sel_hi:[1,0]
	v_pk_mul_f32 v[20:21], v[20:21], v[72:73] op_sel_hi:[1,0]
	v_pk_mul_f32 v[22:23], v[22:23], v[72:73] op_sel_hi:[1,0]
	v_pk_mul_f32 v[16:17], v[16:17], v[72:73] op_sel_hi:[1,0]
	v_pk_mul_f32 v[18:19], v[18:19], v[72:73] op_sel_hi:[1,0]
	v_pk_mul_f32 v[12:13], v[12:13], v[72:73] op_sel_hi:[1,0]
	v_pk_mul_f32 v[14:15], v[14:15], v[72:73] op_sel_hi:[1,0]
	v_pk_mul_f32 v[8:9], v[8:9], v[72:73] op_sel_hi:[1,0]
	v_pk_mul_f32 v[10:11], v[10:11], v[72:73] op_sel_hi:[1,0]
	v_pk_mul_f32 v[4:5], v[4:5], v[72:73] op_sel_hi:[1,0]
	v_pk_mul_f32 v[6:7], v[6:7], v[72:73] op_sel_hi:[1,0]
	v_pk_mul_f32 v[0:1], v[0:1], v[72:73] op_sel_hi:[1,0]
	v_pk_mul_f32 v[2:3], v[2:3], v[72:73] op_sel_hi:[1,0]
	v_cvt_pk_bf16_f32 v68, v68, v69
	v_cvt_pk_bf16_f32 v69, v70, v71
	v_cvt_pk_bf16_f32 v24, v24, v25
	v_cvt_pk_bf16_f32 v25, v26, v27
	v_cvt_pk_bf16_f32 v20, v20, v21
	v_cvt_pk_bf16_f32 v21, v22, v23
	v_cvt_pk_bf16_f32 v16, v16, v17
	v_cvt_pk_bf16_f32 v17, v18, v19
	v_cvt_pk_bf16_f32 v12, v12, v13
	v_cvt_pk_bf16_f32 v13, v14, v15
	v_cvt_pk_bf16_f32 v8, v8, v9
	v_cvt_pk_bf16_f32 v9, v10, v11
	v_cvt_pk_bf16_f32 v4, v4, v5
	v_cvt_pk_bf16_f32 v5, v6, v7
	v_cvt_pk_bf16_f32 v0, v0, v1
	v_cvt_pk_bf16_f32 v1, v2, v3
	s_and_b64 vcc, exec, s[40:41]
	global_store_dwordx2 v[74:75], v[68:69], off
	global_store_dwordx2 v[74:75], v[24:25], off offset:288
	global_store_dwordx2 v[74:75], v[20:21], off offset:320
	global_store_dwordx2 v[74:75], v[16:17], off offset:352
	global_store_dwordx2 v[74:75], v[12:13], off offset:384
	global_store_dwordx2 v[74:75], v[8:9], off offset:416
	global_store_dwordx2 v[74:75], v[4:5], off offset:448
	global_store_dwordx2 v[74:75], v[0:1], off offset:480
	s_cbranch_vccz .LBB0_128
